# baseline (speedup 1.0000x reference)
; #define PG8_STAGE(bufoff, gbase, voff) do { _Pragma("unroll") for (int _i = 0; _i < 2; ++_i) \
;         __builtin_amdgcn_global_load_lds((const unsigned*)((const char*)(gbase) + (voff)[_i]), (PG8_LAS unsigned*)(lds + (bufoff) + ldsw + _i * 8192), 16, 0, 0); } while (0)
; #define PG8_WAIT_V(n) asm volatile("s_waitcnt vmcnt(" #n ")" ::: "memory")
; #define PG8_BAR __builtin_amdgcn_s_barrier()
; template <class Epi, class Sched, bool ALIGN_EPI = false, bool SP2 = false>
; __device__ __forceinline__ void gemm_phase(PG8_LAS unsigned char* lds, const Gemm g, const Sched& S, const Epi& E) {
;     const int tid = threadIdx.x, wid = __builtin_amdgcn_readfirstlane(tid >> 6), lane = tid & 63, wr = wid >> 2, wc = wid & 3, fr = lane & 15, fq = lane >> 4;
;     const int K = g.K;
;     unsigned voffA[2], voffB[2];
; #pragma unroll
;     for (int i = 0; i < 2; ++i) { int R, C; stage_rc(tid * 16 + i * 8192, R, C); const int Rb = Epi::PERM ? ((R & ~31) + perm32(R & 31)) : R;
;         voffA[i] = (unsigned)(R * K + C) * 2u; voffB[i] = (unsigned)(Rb * K + C) * 2u; }
;     const long kstep = (long)(BK * 2);
;     long ks = kstep;
;     const size_t hstep = (size_t)HALF * K * 2;
;     const size_t tstep = 2 * hstep;
;     const unsigned ldsw = (unsigned)wid * 1024u;
;     const int aoff = lds_byte(wr * 64 + fr, fq * 8), boff = lds_byte(wc * 32 + fr, fq * 8);
;     ...
;         PG8_STAGE(PG8_SB(0, 0), cB, voffB); PG8_STAGE(PG8_SB(0, 1), cB + hstep, voffB); PG8_STAGE(PG8_SA(0, 0), cA, voffA); PG8_STAGE(PG8_SA(0, 1), cA + hstep, voffA);
;         if (wr == 1) PG8_BAR;
;         PG8_WAIT_V(2); PG8_BAR;
;         PG8_STAGE(PG8_SB(1, 0), cB + kstep, voffB); PG8_STAGE(PG8_SA(1, 0), cA + kstep, voffA); PG8_STAGE(PG8_SB(1, 1), cB + hstep + kstep, voffB);
;         PG8_WAIT_V(6); PG8_BAR;
.LBB0_343:
	s_lshl_b32 s4, s19, 5
	s_xor_b64 s[26:27], s[26:27], -1
	s_lshl_b32 s33, s18, 13
	s_and_b32 s19, s4, 0x60
	s_add_u32 s70, s58, 0x1b800000
	s_mov_b64 s[44:45], 0x80
	s_addc_u32 s71, s59, 0
	s_add_i32 m0, s98, 0x18000
	v_lshl_add_u64 v[10:11], v[10:11], 0, s[44:45]
	s_waitcnt vmcnt(2)
	s_barrier
	global_load_lds_dwordx4 v[10:11], off
	v_lshl_add_u64 v[6:7], v[6:7], 0, s[44:45]
	s_add_i32 m0, s98, 0x1a000
	s_add_i32 s72, s98, 0x8000
	global_load_lds_dwordx4 v[6:7], off
	v_lshl_add_u64 v[6:7], v[8:9], 0, s[44:45]
	s_mov_b32 m0, s72
	s_add_i32 s73, s98, 0xa000
	global_load_lds_dwordx4 v[6:7], off
	v_lshl_add_u64 v[6:7], v[12:13], 0, s[44:45]
	s_mov_b32 m0, s73
	v_lshl_add_u64 v[4:5], v[4:5], 0, s[44:45]
	global_load_lds_dwordx4 v[6:7], off
	s_add_i32 m0, s98, 0x1c000
	v_lshl_add_u64 v[2:3], v[2:3], 0, s[44:45]
	global_load_lds_dwordx4 v[4:5], off
	s_add_i32 m0, s98, 0x1e000
	s_cmpk_lt_u32 s5, 0x100
	global_load_lds_dwordx4 v[2:3], off
	v_mul_f32_e32 v3, v16, v17
	v_trunc_f32_e32 v3, v3
	v_cvt_u32_f32_e32 v4, v3
	v_fma_f32 v3, -v3, v15, v16
	s_cselect_b64 s[28:29], -1, 0
	s_lshr_b32 s91, s79, s12
	s_lshr_b32 s75, s52, 3
	v_cmp_ge_f32_e64 s[4:5], |v3|, v15
	v_readfirstlane_b32 s12, v4
	s_cmp_lg_u64 s[4:5], 0
	s_addc_u32 s4, s12, 0
	s_and_b32 s76, s4, 0x7ff
	v_cvt_f32_u32_e32 v3, s76
	v_lshlrev_b32_e32 v4, 2, v197
	v_lshl_or_b32 v2, v197, 6, v198
	v_and_b32_e32 v4, 32, v4
	v_bitop3_b32 v4, v2, s33, v4 bitop3:0xde
	v_rcp_iflag_f32_e32 v2, v3
	v_rcp_iflag_f32_e32 v3, v18
	s_sub_i32 s4, 0, s76
	s_waitcnt vmcnt(6)
	v_mul_f32_e32 v2, 0x4f7ffffe, v2
	v_cvt_u32_f32_e32 v2, v2
	v_lshl_or_b32 v144, s18, 6, v197
	v_lshl_or_b32 v145, s19, 7, v199
	v_add_u32_e32 v242, 0x10000, v145
	v_or_b32_e32 v146, s19, v192
	v_readfirstlane_b32 s5, v2
	v_mul_f32_e32 v2, 0x4f7ffffe, v14
	v_cvt_u32_f32_e32 v2, v2
	s_mul_i32 s4, s4, s5
	s_mul_hi_u32 s4, s5, s4
	s_add_i32 s77, s5, s4
	v_readfirstlane_b32 s5, v2
	v_mul_f32_e32 v2, 0x4f7ffffe, v3
	v_cvt_u32_f32_e32 v2, v2
	s_sub_i32 s4, 0, s7
	s_mul_i32 s4, s4, s5
	s_mul_hi_u32 s4, s5, s4
	s_add_i32 s69, s5, s4
	s_sub_i32 s4, 0, s78
	v_readfirstlane_b32 s5, v2
	s_mul_i32 s4, s4, s5
	v_add_lshl_u32 v2, v200, v19, 1
	v_mov_b32_e32 v3, v1
	s_mul_hi_u32 s4, s5, s4
	v_lshl_add_u64 v[136:137], s[16:17], 0, v[2:3]
	v_add_lshl_u32 v2, v200, v20, 1
	s_mov_b32 s18, 0
	s_add_i32 s5, s5, s4
	v_lshl_add_u64 v[138:139], s[16:17], 0, v[2:3]
	v_add_u32_e32 v147, 0, v4
	s_barrier
	s_mov_b64 s[82:83], 0
	s_branch .LBB0_346

; #define PG8_STAGE(bufoff, gbase, voff) do { _Pragma("unroll") for (int _i = 0; _i < 2; ++_i) \
;         __builtin_amdgcn_global_load_lds((const unsigned*)((const char*)(gbase) + (voff)[_i]), (PG8_LAS unsigned*)(lds + (bufoff) + ldsw + _i * 8192), 16, 0, 0); } while (0)
; #define PG8_LDA(dst, b, h) do { _Pragma("unroll") for (int m = 0; m < 4; ++m) _Pragma("unroll") for (int k = 0; k < 2; ++k) dst[m][k] = *(const PG8_LAS bf16x8*)(lds + PG8_SA(b, h) + aoff + m * 2048 + k * 1024); } while (0)
; #define PG8_LDB(dst, b, h) do { _Pragma("unroll") for (int n = 0; n < 2; ++n) _Pragma("unroll") for (int k = 0; k < 2; ++k) dst[n][k] = *(const PG8_LAS bf16x8*)(lds + PG8_SB(b, h) + boff + n * 2048 + k * 1024); } while (0)
; #define PG8_MMA(ai, bj, At, Bt) do { __builtin_amdgcn_s_setprio(1); _Pragma("unroll") for (int m = 0; m < 4; ++m) _Pragma("unroll") for (int n = 0; n < 2; ++n) _Pragma("unroll") for (int k = 0; k < 2; ++k) \
;         acc[ai][bj][m][n] = __builtin_amdgcn_mfma_f32_16x16x32_bf16(Bt[n][k], At[m][k], acc[ai][bj][m][n], 0, 0, 0); __builtin_amdgcn_s_setprio(0); } while (0)
; #define PG8_WAIT_V(n) asm volatile("s_waitcnt vmcnt(" #n ")" ::: "memory")
; #define PG8_WAIT_L(n) asm volatile("s_waitcnt lgkmcnt(" #n ")" ::: "memory")
; #define PG8_BAR __builtin_amdgcn_s_barrier()
; #define PG8_SCHED __builtin_amdgcn_sched_barrier(0)
; template <class Epi, class Sched, bool ALIGN_EPI = false, bool SP2 = false>
; __device__ __forceinline__ void gemm_phase(PG8_LAS unsigned char* lds, const Gemm g, const Sched& S, const Epi& E) {
;     ...
;             PG8_LDB(B0, 0, 0); PG8_LDB(B1, 0, 1); PG8_SCHED; PG8_LDA(At, 0, 0); PG8_STAGE(PG8_SA(1, 1), a1 + hstep, voffA);
;             PG8_WAIT_V(8); PG8_WAIT_L(0); PG8_BAR; PG8_MMA(0, 0, At, B0); PG8_MMA(0, 1, At, B1); PG8_BAR; PG8_SCHED;
;             PG8_LDA(At, 0, 1); PG8_STAGE(PG8_SB(0, 0), b2, voffB); PG8_STAGE(PG8_SB(0, 1), b2 + hstep, voffB); PG8_STAGE(PG8_SA(0, 0), a2, voffA);
;             PG8_WAIT_V(8); PG8_WAIT_L(0); PG8_BAR; PG8_MMA(1, 0, At, B0); PG8_MMA(1, 1, At, B1); PG8_BAR; PG8_SCHED;
;     ...
;         cur = nxt; cA = nA; cB = nB; ks = nks; ++ui;
;         if constexpr (ALIGN_EPI) { if (wr == 1) PG8_BAR; }
.LBB0_354:
	s_add_i32 s88, s13, -2
	s_lshl_b64 s[48:49], s[44:45], 1
	s_add_u32 s87, s50, s48
	v_lshl_add_u64 v[2:3], s[56:57], 0, v[136:137]
	s_addc_u32 s33, s51, s49
	v_lshl_add_u64 v[140:141], v[2:3], 0, s[44:45]
	v_lshl_add_u64 v[2:3], s[56:57], 0, v[138:139]
	s_add_u32 s18, s56, s48
	v_lshl_add_u64 v[142:143], v[2:3], 0, s[44:45]
	s_addc_u32 s19, s57, s49
	s_mov_b32 s80, 0
	s_mov_b64 s[50:51], 0
	s_andn2_b64 vcc, exec, s[82:83]
	s_cbranch_vccnz .Lgemm_nobar
	s_barrier
.Lgemm_nobar:
	s_branch .LBB0_356
.LBB0_355:
	s_add_i32 s80, s80, 2
	s_add_u32 s82, s62, s60
	s_addc_u32 s83, s63, s61
	ds_read_b128 v[148:151], v242
	ds_read_b128 v[152:155], v242 offset:1024
	ds_read_b128 v[156:159], v242 offset:2048
	ds_read_b128 v[160:163], v242 offset:3072
	ds_read_b128 v[164:167], v242 offset:16384
	ds_read_b128 v[168:171], v242 offset:17408
	ds_read_b128 v[172:175], v242 offset:18432
	ds_read_b128 v[176:179], v242 offset:19456
	v_lshl_add_u64 v[232:233], v[140:141], 0, s[50:51]
	s_add_i32 m0, s98, 0xc000
	ds_read_b128 v[182:185], v147
	ds_read_b128 v[186:189], v147 offset:1024
	ds_read_b128 v[208:211], v147 offset:2048
	ds_read_b128 v[212:215], v147 offset:3072
	ds_read_b128 v[216:219], v147 offset:4096
	ds_read_b128 v[220:223], v147 offset:5120
	ds_read_b128 v[224:227], v147 offset:6144
	ds_read_b128 v[228:231], v147 offset:7168
	global_load_lds_dwordx4 v[232:233], off
	v_lshl_add_u64 v[232:233], v[142:143], 0, s[50:51]
	s_add_i32 m0, s98, 0xe000
	s_nop 0
	global_load_lds_dwordx4 v[232:233], off
	s_waitcnt vmcnt(8)
	s_waitcnt lgkmcnt(0)
	s_barrier
	s_setprio 1
	v_mfma_f32_16x16x32_bf16 v[126:129], v[148:151], v[182:185], 0
	v_mfma_f32_16x16x32_bf16 v[122:125], v[156:159], v[182:185], 0
	v_mfma_f32_16x16x32_bf16 v[118:121], v[148:151], v[208:211], 0
	v_mfma_f32_16x16x32_bf16 v[110:113], v[156:159], v[208:211], 0
	v_mfma_f32_16x16x32_bf16 v[102:105], v[148:151], v[216:219], 0
	v_mfma_f32_16x16x32_bf16 v[94:97], v[156:159], v[216:219], 0
	v_mfma_f32_16x16x32_bf16 v[86:89], v[148:151], v[224:227], 0
	v_mfma_f32_16x16x32_bf16 v[78:81], v[156:159], v[224:227], 0
	v_mfma_f32_16x16x32_bf16 v[126:129], v[152:155], v[186:189], v[126:129]
	v_mfma_f32_16x16x32_bf16 v[122:125], v[160:163], v[186:189], v[122:125]
	v_mfma_f32_16x16x32_bf16 v[118:121], v[152:155], v[212:215], v[118:121]
	v_mfma_f32_16x16x32_bf16 v[110:113], v[160:163], v[212:215], v[110:113]
	v_mfma_f32_16x16x32_bf16 v[102:105], v[152:155], v[220:223], v[102:105]
	v_mfma_f32_16x16x32_bf16 v[94:97], v[160:163], v[220:223], v[94:97]
	v_mfma_f32_16x16x32_bf16 v[86:89], v[152:155], v[228:231], v[86:89]
	v_mfma_f32_16x16x32_bf16 v[78:81], v[160:163], v[228:231], v[78:81]
	v_mfma_f32_16x16x32_bf16 v[114:117], v[164:167], v[182:185], 0
	v_mfma_f32_16x16x32_bf16 v[106:109], v[172:175], v[182:185], 0
	v_mfma_f32_16x16x32_bf16 v[98:101], v[164:167], v[208:211], 0
	v_mfma_f32_16x16x32_bf16 v[90:93], v[172:175], v[208:211], 0
	v_mfma_f32_16x16x32_bf16 v[82:85], v[164:167], v[216:219], 0
	v_mfma_f32_16x16x32_bf16 v[74:77], v[172:175], v[216:219], 0
	v_mfma_f32_16x16x32_bf16 v[70:73], v[164:167], v[224:227], 0
	v_mfma_f32_16x16x32_bf16 v[66:69], v[172:175], v[224:227], 0
	v_mfma_f32_16x16x32_bf16 v[114:117], v[168:171], v[186:189], v[114:117]
	v_mfma_f32_16x16x32_bf16 v[106:109], v[176:179], v[186:189], v[106:109]
	v_mfma_f32_16x16x32_bf16 v[98:101], v[168:171], v[212:215], v[98:101]
	v_mfma_f32_16x16x32_bf16 v[90:93], v[176:179], v[212:215], v[90:93]
	v_mfma_f32_16x16x32_bf16 v[82:85], v[168:171], v[220:223], v[82:85]
	v_mfma_f32_16x16x32_bf16 v[74:77], v[176:179], v[220:223], v[74:77]
	v_mfma_f32_16x16x32_bf16 v[70:73], v[168:171], v[228:231], v[70:73]
	v_mfma_f32_16x16x32_bf16 v[66:69], v[176:179], v[228:231], v[66:69]
	s_setprio 0
	s_barrier
	s_add_i32 m0, s97, 0x10000
	ds_read_b128 v[182:185], v147 offset:16384
	ds_read_b128 v[186:189], v147 offset:17408
	ds_read_b128 v[208:211], v147 offset:18432
	ds_read_b128 v[212:215], v147 offset:19456
	ds_read_b128 v[216:219], v147 offset:20480
	ds_read_b128 v[220:223], v147 offset:21504
	ds_read_b128 v[224:227], v147 offset:22528
	ds_read_b128 v[228:231], v147 offset:23552
	global_load_lds_dwordx4 v0, s[56:57]
	s_add_i32 m0, s97, 0x12000
	s_add_u32 s38, s56, s16
	s_addc_u32 s39, s57, 0
	global_load_lds_dwordx4 v134, s[56:57]
	s_add_i32 m0, s97, 0x14000
	s_nop 0
	global_load_lds_dwordx4 v0, s[38:39]
	s_add_i32 m0, s97, 0x16000
	s_nop 0
	global_load_lds_dwordx4 v134, s[38:39]
	s_mov_b32 m0, s98
	s_nop 0
	global_load_lds_dwordx4 v130, s[62:63]
	s_mov_b32 m0, s99
	s_nop 0
	global_load_lds_dwordx4 v132, s[62:63]
	s_waitcnt vmcnt(8)
	s_waitcnt lgkmcnt(0)
	s_barrier
; #define PG8_STAGE(bufoff, gbase, voff) do { _Pragma("unroll") for (int _i = 0; _i < 2; ++_i) \
;         __builtin_amdgcn_global_load_lds((const unsigned*)((const char*)(gbase) + (voff)[_i]), (PG8_LAS unsigned*)(lds + (bufoff) + ldsw + _i * 8192), 16, 0, 0); } while (0)
; #define PG8_LDA(dst, b, h) do { _Pragma("unroll") for (int m = 0; m < 4; ++m) _Pragma("unroll") for (int k = 0; k < 2; ++k) dst[m][k] = *(const PG8_LAS bf16x8*)(lds + PG8_SA(b, h) + aoff + m * 2048 + k * 1024); } while (0)
; #define PG8_LDB(dst, b, h) do { _Pragma("unroll") for (int n = 0; n < 2; ++n) _Pragma("unroll") for (int k = 0; k < 2; ++k) dst[n][k] = *(const PG8_LAS bf16x8*)(lds + PG8_SB(b, h) + boff + n * 2048 + k * 1024); } while (0)
; #define PG8_MMA(ai, bj, At, Bt) do { __builtin_amdgcn_s_setprio(1); _Pragma("unroll") for (int m = 0; m < 4; ++m) _Pragma("unroll") for (int n = 0; n < 2; ++n) _Pragma("unroll") for (int k = 0; k < 2; ++k) \
;         acc[ai][bj][m][n] = __builtin_amdgcn_mfma_f32_16x16x32_bf16(Bt[n][k], At[m][k], acc[ai][bj][m][n], 0, 0, 0); __builtin_amdgcn_s_setprio(0); } while (0)
; #define PG8_WAIT_V(n) asm volatile("s_waitcnt vmcnt(" #n ")" ::: "memory")
; #define PG8_WAIT_L(n) asm volatile("s_waitcnt lgkmcnt(" #n ")" ::: "memory")
; #define PG8_BAR __builtin_amdgcn_s_barrier()
; #define PG8_SCHED __builtin_amdgcn_sched_barrier(0)
; template <class Epi, class Sched, bool ALIGN_EPI = false, bool SP2 = false>
; __device__ __forceinline__ void gemm_phase(PG8_LAS unsigned char* lds, const Gemm g, const Sched& S, const Epi& E) {
;     ...
;             PG8_WAIT_V(8); PG8_WAIT_L(0); PG8_BAR; PG8_MMA(1, 0, At, B0); PG8_MMA(1, 1, At, B1); PG8_BAR; PG8_SCHED;
;             PG8_LDB(B0, 1, 0); PG8_LDB(B1, 1, 1); PG8_SCHED; PG8_LDA(At, 1, 0); PG8_STAGE(PG8_SA(0, 1), a2 + hstep, voffA);
;             PG8_WAIT_V(8); PG8_WAIT_L(0); PG8_BAR; PG8_MMA(0, 0, At, B0); PG8_MMA(0, 1, At, B1); PG8_BAR; PG8_SCHED;
;             PG8_LDA(At, 1, 1); PG8_STAGE(PG8_SB(1, 0), b3, voffB); PG8_STAGE(PG8_SB(1, 1), b3 + hstep, voffB); PG8_STAGE(PG8_SA(1, 0), a3, voffA);
;             PG8_WAIT_V(8); PG8_WAIT_L(0); PG8_BAR; PG8_MMA(1, 0, At, B0); PG8_MMA(1, 1, At, B1); PG8_BAR; PG8_SCHED;
	s_setprio 1
	v_mfma_f32_16x16x32_bf16 v[62:65], v[148:151], v[182:185], 0
	v_mfma_f32_16x16x32_bf16 v[58:61], v[156:159], v[182:185], 0
	v_mfma_f32_16x16x32_bf16 v[54:57], v[148:151], v[208:211], 0
	v_mfma_f32_16x16x32_bf16 v[46:49], v[156:159], v[208:211], 0
	v_mfma_f32_16x16x32_bf16 v[38:41], v[148:151], v[216:219], 0
	v_mfma_f32_16x16x32_bf16 v[30:33], v[156:159], v[216:219], 0
	v_mfma_f32_16x16x32_bf16 v[22:25], v[148:151], v[224:227], 0
	v_mfma_f32_16x16x32_bf16 v[14:17], v[156:159], v[224:227], 0
	v_mfma_f32_16x16x32_bf16 v[62:65], v[152:155], v[186:189], v[62:65]
	v_mfma_f32_16x16x32_bf16 v[58:61], v[160:163], v[186:189], v[58:61]
	v_mfma_f32_16x16x32_bf16 v[54:57], v[152:155], v[212:215], v[54:57]
	v_mfma_f32_16x16x32_bf16 v[46:49], v[160:163], v[212:215], v[46:49]
	v_mfma_f32_16x16x32_bf16 v[38:41], v[152:155], v[220:223], v[38:41]
	v_mfma_f32_16x16x32_bf16 v[30:33], v[160:163], v[220:223], v[30:33]
	v_mfma_f32_16x16x32_bf16 v[22:25], v[152:155], v[228:231], v[22:25]
	v_mfma_f32_16x16x32_bf16 v[14:17], v[160:163], v[228:231], v[14:17]
	v_mfma_f32_16x16x32_bf16 v[50:53], v[164:167], v[182:185], 0
	v_mfma_f32_16x16x32_bf16 v[42:45], v[172:175], v[182:185], 0
	v_mfma_f32_16x16x32_bf16 v[34:37], v[164:167], v[208:211], 0
	v_mfma_f32_16x16x32_bf16 v[26:29], v[172:175], v[208:211], 0
	v_mfma_f32_16x16x32_bf16 v[18:21], v[164:167], v[216:219], 0
	v_mfma_f32_16x16x32_bf16 v[10:13], v[172:175], v[216:219], 0
	v_mfma_f32_16x16x32_bf16 v[6:9], v[164:167], v[224:227], 0
	v_mfma_f32_16x16x32_bf16 v[2:5], v[172:175], v[224:227], 0
	v_mfma_f32_16x16x32_bf16 v[50:53], v[168:171], v[186:189], v[50:53]
	v_mfma_f32_16x16x32_bf16 v[42:45], v[176:179], v[186:189], v[42:45]
	v_mfma_f32_16x16x32_bf16 v[34:37], v[168:171], v[212:215], v[34:37]
	v_mfma_f32_16x16x32_bf16 v[26:29], v[176:179], v[212:215], v[26:29]
	v_mfma_f32_16x16x32_bf16 v[18:21], v[168:171], v[220:223], v[18:21]
	v_mfma_f32_16x16x32_bf16 v[10:13], v[176:179], v[220:223], v[10:13]
	v_mfma_f32_16x16x32_bf16 v[6:9], v[168:171], v[228:231], v[6:9]
	v_mfma_f32_16x16x32_bf16 v[2:5], v[176:179], v[228:231], v[2:5]
	s_setprio 0
	s_barrier
	ds_read_b128 v[148:151], v242 offset:32768
	ds_read_b128 v[152:155], v242 offset:33792
	ds_read_b128 v[156:159], v242 offset:34816
	ds_read_b128 v[160:163], v242 offset:35840
	ds_read_b128 v[164:167], v242 offset:49152
	ds_read_b128 v[168:171], v242 offset:50176
	ds_read_b128 v[172:175], v242 offset:51200
	ds_read_b128 v[176:179], v242 offset:52224
	s_add_u32 s38, s62, s16
	s_addc_u32 s39, s63, 0
	s_mov_b32 m0, s68
	ds_read_b128 v[182:185], v147 offset:32768
	ds_read_b128 v[186:189], v147 offset:33792
	ds_read_b128 v[208:211], v147 offset:34816
	ds_read_b128 v[212:215], v147 offset:35840
	ds_read_b128 v[216:219], v147 offset:36864
	ds_read_b128 v[220:223], v147 offset:37888
	ds_read_b128 v[224:227], v147 offset:38912
	ds_read_b128 v[228:231], v147 offset:39936
	global_load_lds_dwordx4 v130, s[38:39]
	s_mov_b32 m0, s64
	s_nop 0
	global_load_lds_dwordx4 v132, s[38:39]
	s_waitcnt vmcnt(8)
	s_waitcnt lgkmcnt(0)
	s_barrier
	s_setprio 1
	v_mfma_f32_16x16x32_bf16 v[126:129], v[148:151], v[182:185], v[126:129]
	v_mfma_f32_16x16x32_bf16 v[122:125], v[156:159], v[182:185], v[122:125]
	v_mfma_f32_16x16x32_bf16 v[118:121], v[148:151], v[208:211], v[118:121]
	v_mfma_f32_16x16x32_bf16 v[110:113], v[156:159], v[208:211], v[110:113]
	v_mfma_f32_16x16x32_bf16 v[102:105], v[148:151], v[216:219], v[102:105]
	v_mfma_f32_16x16x32_bf16 v[94:97], v[156:159], v[216:219], v[94:97]
	v_mfma_f32_16x16x32_bf16 v[86:89], v[148:151], v[224:227], v[86:89]
	v_mfma_f32_16x16x32_bf16 v[78:81], v[156:159], v[224:227], v[78:81]
	v_mfma_f32_16x16x32_bf16 v[126:129], v[152:155], v[186:189], v[126:129]
	v_mfma_f32_16x16x32_bf16 v[122:125], v[160:163], v[186:189], v[122:125]
	v_mfma_f32_16x16x32_bf16 v[118:121], v[152:155], v[212:215], v[118:121]
	v_mfma_f32_16x16x32_bf16 v[110:113], v[160:163], v[212:215], v[110:113]
	v_mfma_f32_16x16x32_bf16 v[102:105], v[152:155], v[220:223], v[102:105]
	v_mfma_f32_16x16x32_bf16 v[94:97], v[160:163], v[220:223], v[94:97]
	v_mfma_f32_16x16x32_bf16 v[86:89], v[152:155], v[228:231], v[86:89]
	v_mfma_f32_16x16x32_bf16 v[78:81], v[160:163], v[228:231], v[78:81]
	v_mfma_f32_16x16x32_bf16 v[114:117], v[164:167], v[182:185], v[114:117]
	v_mfma_f32_16x16x32_bf16 v[106:109], v[172:175], v[182:185], v[106:109]
	v_mfma_f32_16x16x32_bf16 v[98:101], v[164:167], v[208:211], v[98:101]
	v_mfma_f32_16x16x32_bf16 v[90:93], v[172:175], v[208:211], v[90:93]
	v_mfma_f32_16x16x32_bf16 v[82:85], v[164:167], v[216:219], v[82:85]
	v_mfma_f32_16x16x32_bf16 v[74:77], v[172:175], v[216:219], v[74:77]
	v_mfma_f32_16x16x32_bf16 v[70:73], v[164:167], v[224:227], v[70:73]
	v_mfma_f32_16x16x32_bf16 v[66:69], v[172:175], v[224:227], v[66:69]
	v_mfma_f32_16x16x32_bf16 v[114:117], v[168:171], v[186:189], v[114:117]
	v_mfma_f32_16x16x32_bf16 v[106:109], v[176:179], v[186:189], v[106:109]
	v_mfma_f32_16x16x32_bf16 v[98:101], v[168:171], v[212:215], v[98:101]
	v_mfma_f32_16x16x32_bf16 v[90:93], v[176:179], v[212:215], v[90:93]
	v_mfma_f32_16x16x32_bf16 v[82:85], v[168:171], v[220:223], v[82:85]
	v_mfma_f32_16x16x32_bf16 v[74:77], v[176:179], v[220:223], v[74:77]
	v_mfma_f32_16x16x32_bf16 v[70:73], v[168:171], v[228:231], v[70:73]
	v_mfma_f32_16x16x32_bf16 v[66:69], v[176:179], v[228:231], v[66:69]
	s_setprio 0
	s_barrier
	s_add_u32 s38, s56, s60
	s_addc_u32 s39, s57, s61
	s_add_i32 m0, s97, 0x18000
	ds_read_b128 v[182:185], v147 offset:49152
	ds_read_b128 v[186:189], v147 offset:50176
	ds_read_b128 v[208:211], v147 offset:51200
	ds_read_b128 v[212:215], v147 offset:52224
	ds_read_b128 v[216:219], v147 offset:53248
	ds_read_b128 v[220:223], v147 offset:54272
	ds_read_b128 v[224:227], v147 offset:55296
	ds_read_b128 v[228:231], v147 offset:56320
	global_load_lds_dwordx4 v0, s[38:39]
	s_add_i32 m0, s97, 0x1a000
	s_nop 0
	global_load_lds_dwordx4 v134, s[38:39]
	s_add_u32 s38, s38, s16
	s_addc_u32 s39, s39, 0
	s_add_i32 m0, s97, 0x1c000
	global_load_lds_dwordx4 v0, s[38:39]
	s_add_i32 m0, s97, 0x1e000
	s_nop 0
	global_load_lds_dwordx4 v134, s[38:39]
	s_mov_b32 m0, s72
	s_nop 0
	global_load_lds_dwordx4 v130, s[82:83]
	s_mov_b32 m0, s73
	s_nop 0
	global_load_lds_dwordx4 v132, s[82:83]
	s_add_u32 s50, s50, s48
	s_addc_u32 s51, s51, s49
	s_cmp_ge_u32 s80, s13
	s_cselect_b64 vcc, -1, 0
	s_cbranch_scc1 .Lgemm_ctl_done_p
	s_cmp_eq_u32 s88, s80
	s_cbranch_scc1 .Lgemm_ctl_last_p
	s_add_u32 s62, s18, s50
	s_addc_u32 s63, s19, s51
	s_add_u32 s56, s87, s50
	s_addc_u32 s57, s33, s51
	s_mov_b64 s[60:61], s[44:45]
	s_branch .Lgemm_ctl_join_p

; __device__ __forceinline__ unsigned cvt_pk_bf16(float lo, float hi) { unsigned r; asm volatile("v_cvt_pk_bf16_f32 %0, %1, %2" : "=v"(r) : "v"(lo), "v"(hi)); return r; }
; #define PG8_BAR __builtin_amdgcn_s_barrier()
;     __device__ __forceinline__ void operator()(const f32x4 (&acc)[2][2][4][2], const Unit& u, int wr, int wc, int fr, int fq) const {
;     ...
;             bf16_t* Pp = P + (size_t)u.part * pstride; const int col0 = u.pn * BM + wc * 32 + 8 * fq;
; #pragma unroll
;             for (int ai = 0; ai < 2; ++ai)
; #pragma unroll
;                 for (int m = 0; m < 4; ++m) { bf16_t* rowp = Pp + (size_t)(row0 + ai * HALF + m * 16 - prow0) * ldc + col0;
; #pragma unroll
;                     for (int bj = 0; bj < 2; ++bj) { const f32x4 v0 = acc[ai][bj][m][0], v1 = acc[ai][bj][m][1];
;                         u32x4 w; w.x = cvt_pk_bf16(v0[0], v0[1]); w.y = cvt_pk_bf16(v0[2], v0[3]); w.z = cvt_pk_bf16(v1[0], v1[1]); w.w = cvt_pk_bf16(v1[2], v1[3]);
;                         *(u32x4*)(rowp + bj * HALF) = w; } }
; template <class Epi, class Sched, bool ALIGN_EPI = false, bool SP2 = false>
; __device__ __forceinline__ void gemm_phase(PG8_LAS unsigned char* lds, const Gemm g, const Sched& S, const Epi& E) {
;     ...
;         if constexpr (ALIGN_EPI) { if (wr == 1) PG8_BAR; }
.LBB0_370:
	s_mov_b32 s31, s89
	s_lshl_b64 s[18:19], s[30:31], 23
	s_add_u32 s18, s70, s18
	v_lshl_or_b32 v140, s67, 8, v146
	s_addc_u32 s19, s71, s19
	v_ashrrev_i32_e32 v141, 31, v140
	v_add_u32_e32 v142, 0xffffc000, v148
	v_lshl_add_u64 v[140:141], v[140:141], 1, s[18:19]
	v_mad_i64_i32 v[142:143], s[18:19], s20, v142, 0
	v_lshl_add_u64 v[142:143], v[142:143], 1, v[140:141]
	v_cvt_pk_bf16_f32 v126, v126, v127
	v_cvt_pk_bf16_f32 v127, v128, v129
	v_cvt_pk_bf16_f32 v128, v122, v123
	v_cvt_pk_bf16_f32 v129, v124, v125
	global_store_dwordx4 v[142:143], v[126:129], off sc1
	v_cvt_pk_bf16_f32 v114, v114, v115
	v_cvt_pk_bf16_f32 v115, v116, v117
	v_cvt_pk_bf16_f32 v116, v106, v107
	v_add_u32_e32 v106, 0xffffc010, v148
	v_mad_i64_i32 v[106:107], s[18:19], s20, v106, 0
	v_cvt_pk_bf16_f32 v117, v108, v109
	global_store_dwordx4 v[142:143], v[114:117], off offset:256 sc1
	s_nop 1
	v_lshl_add_u64 v[114:115], v[106:107], 1, v[140:141]
	v_cvt_pk_bf16_f32 v106, v118, v119
	v_cvt_pk_bf16_f32 v107, v120, v121
	v_cvt_pk_bf16_f32 v108, v110, v111
	v_cvt_pk_bf16_f32 v109, v112, v113
	global_store_dwordx4 v[114:115], v[106:109], off sc1
	v_cvt_pk_bf16_f32 v98, v98, v99
	v_cvt_pk_bf16_f32 v99, v100, v101
	v_cvt_pk_bf16_f32 v100, v90, v91
	v_add_u32_e32 v90, 0xffffc020, v148
	v_mad_i64_i32 v[90:91], s[18:19], s20, v90, 0
	v_cvt_pk_bf16_f32 v101, v92, v93
	global_store_dwordx4 v[114:115], v[98:101], off offset:256 sc1
	s_nop 1
	v_lshl_add_u64 v[98:99], v[90:91], 1, v[140:141]
	v_cvt_pk_bf16_f32 v90, v102, v103
	v_cvt_pk_bf16_f32 v91, v104, v105
	v_cvt_pk_bf16_f32 v92, v94, v95
	v_cvt_pk_bf16_f32 v93, v96, v97
	global_store_dwordx4 v[98:99], v[90:93], off sc1
	v_cvt_pk_bf16_f32 v82, v82, v83
	v_cvt_pk_bf16_f32 v83, v84, v85
	v_cvt_pk_bf16_f32 v84, v74, v75
	v_add_u32_e32 v74, 0xffffc030, v148
	v_mad_i64_i32 v[74:75], s[18:19], s20, v74, 0
	v_cvt_pk_bf16_f32 v85, v76, v77
	global_store_dwordx4 v[98:99], v[82:85], off offset:256 sc1
	s_nop 1
	v_lshl_add_u64 v[82:83], v[74:75], 1, v[140:141]
	v_cvt_pk_bf16_f32 v74, v86, v87
	v_cvt_pk_bf16_f32 v75, v88, v89
	v_cvt_pk_bf16_f32 v76, v78, v79
	v_cvt_pk_bf16_f32 v77, v80, v81
	global_store_dwordx4 v[82:83], v[74:77], off sc1
	v_cvt_pk_bf16_f32 v70, v70, v71
	v_cvt_pk_bf16_f32 v71, v72, v73
	v_cvt_pk_bf16_f32 v72, v66, v67
	v_add_u32_e32 v66, 0xffffc080, v148
	v_mad_i64_i32 v[66:67], s[18:19], s20, v66, 0
	v_lshl_add_u64 v[66:67], v[66:67], 1, v[140:141]
	v_cvt_pk_bf16_f32 v73, v68, v69
	global_store_dwordx4 v[82:83], v[70:73], off offset:256 sc1
	v_cvt_pk_bf16_f32 v62, v62, v63
	v_cvt_pk_bf16_f32 v63, v64, v65
	v_cvt_pk_bf16_f32 v64, v58, v59
	v_cvt_pk_bf16_f32 v65, v60, v61
	global_store_dwordx4 v[66:67], v[62:65], off sc1
	v_cvt_pk_bf16_f32 v50, v50, v51
	v_cvt_pk_bf16_f32 v51, v52, v53
	v_cvt_pk_bf16_f32 v52, v42, v43
	v_add_u32_e32 v42, 0xffffc090, v148
	v_mad_i64_i32 v[42:43], s[18:19], s20, v42, 0
	v_cvt_pk_bf16_f32 v53, v44, v45
	global_store_dwordx4 v[66:67], v[50:53], off offset:256 sc1
	s_nop 1
	v_lshl_add_u64 v[50:51], v[42:43], 1, v[140:141]
	v_cvt_pk_bf16_f32 v42, v54, v55
	v_cvt_pk_bf16_f32 v43, v56, v57
	v_cvt_pk_bf16_f32 v44, v46, v47
	v_cvt_pk_bf16_f32 v45, v48, v49
	global_store_dwordx4 v[50:51], v[42:45], off sc1
	v_cvt_pk_bf16_f32 v34, v34, v35
	v_cvt_pk_bf16_f32 v35, v36, v37
	v_cvt_pk_bf16_f32 v36, v26, v27
	v_add_u32_e32 v26, 0xffffc0a0, v148
	v_mad_i64_i32 v[26:27], s[18:19], s20, v26, 0
	v_cvt_pk_bf16_f32 v37, v28, v29
	global_store_dwordx4 v[50:51], v[34:37], off offset:256 sc1
	s_nop 1
	v_lshl_add_u64 v[34:35], v[26:27], 1, v[140:141]
	v_cvt_pk_bf16_f32 v26, v38, v39
	v_cvt_pk_bf16_f32 v27, v40, v41
	v_cvt_pk_bf16_f32 v28, v30, v31
	v_cvt_pk_bf16_f32 v29, v32, v33
	global_store_dwordx4 v[34:35], v[26:29], off sc1
	v_cvt_pk_bf16_f32 v18, v18, v19
	v_cvt_pk_bf16_f32 v19, v20, v21
	v_cvt_pk_bf16_f32 v20, v10, v11
	v_add_u32_e32 v10, 0xffffc0b0, v148
	v_mad_i64_i32 v[10:11], s[18:19], s20, v10, 0
	v_cvt_pk_bf16_f32 v21, v12, v13
	global_store_dwordx4 v[34:35], v[18:21], off offset:256 sc1
	s_nop 1
	v_lshl_add_u64 v[18:19], v[10:11], 1, v[140:141]
	v_cvt_pk_bf16_f32 v10, v22, v23
	v_cvt_pk_bf16_f32 v11, v24, v25
	v_cvt_pk_bf16_f32 v12, v14, v15
	v_cvt_pk_bf16_f32 v13, v16, v17
	global_store_dwordx4 v[18:19], v[10:13], off sc1
	v_cvt_pk_bf16_f32 v6, v6, v7
	v_cvt_pk_bf16_f32 v7, v8, v9
	v_cvt_pk_bf16_f32 v8, v2, v3
	v_cvt_pk_bf16_f32 v9, v4, v5
	global_store_dwordx4 v[18:19], v[6:9], off offset:256 sc1
	s_and_b64 vcc, exec, s[40:41]
	s_mov_b64 s[30:31], -1
	s_cbranch_vccnz .LBB0_345
.LBB0_371:
	s_mov_b64 s[82:83], s[24:25]
	s_branch .LBB0_344
